# v111 + XCD-barrier entry: the two LDS state reads issued back to back with one wait (11 inlined seam sites)
# baseline (speedup 1.0000x reference)
.LBB0_153:
	v_readlane_b32 s0, v254, 49
	s_cmp_gt_i32 s0, 1
	s_mov_b64 s[0:1], -1
	s_cbranch_scc0 .LBB0_207
	s_waitcnt vmcnt(0)
	s_waitcnt vmcnt(0) lgkmcnt(0)
	s_barrier
	s_mov_b64 s[0:1], exec
	v_readlane_b32 s10, v252, 21
	v_readlane_b32 s11, v252, 22
	s_and_b64 s[10:11], s[0:1], s[10:11]
	s_mov_b64 exec, s[10:11]
	s_cbranch_execz .LBB0_206
	s_mov_b64 s[10:11], src_shared_base
	v_mov_b32_e32 v199, s11
	s_waitcnt vmcnt(0) expcnt(0) lgkmcnt(0)
	flat_load_dword v2, v[198:199] sc0 sc1
	v_mov_b32_e32 v201, s11
	flat_load_dword v0, v[200:201] sc0 sc1
	s_waitcnt vmcnt(0) lgkmcnt(0)
	v_cmp_eq_u32_e32 vcc, 0, v2
	s_and_saveexec_b64 s[10:11], vcc
	s_cbranch_execz .LBB0_170
	s_mov_b32 s25, 1
	s_branch .LBB0_158

.LBB0_287:
	v_readlane_b32 s0, v254, 49
	s_cmp_gt_i32 s0, 0
	s_mov_b64 s[0:1], -1
	s_cbranch_scc0 .LBB0_341
	s_waitcnt vmcnt(0)
	s_barrier
	s_mov_b64 s[0:1], exec
	v_readlane_b32 s40, v252, 21
	v_readlane_b32 s41, v252, 22
	s_and_b64 s[40:41], s[0:1], s[40:41]
	s_mov_b64 exec, s[40:41]
	s_cbranch_execz .LBB0_340
	s_mov_b64 s[40:41], src_shared_base
	v_mov_b32_e32 v199, s41
	s_waitcnt vmcnt(0) expcnt(0) lgkmcnt(0)
	flat_load_dword v2, v[198:199] sc0 sc1
	v_mov_b32_e32 v201, s41
	flat_load_dword v0, v[200:201] sc0 sc1
	s_waitcnt vmcnt(0) lgkmcnt(0)
	v_cmp_eq_u32_e32 vcc, 0, v2
	s_and_saveexec_b64 s[40:41], vcc
	s_cbranch_execz .LBB0_304
	s_mov_b32 s34, 1
	s_branch .LBB0_292

.LBB0_485:
	v_readlane_b32 s0, v254, 49
	s_cmp_gt_i32 s0, -1
	s_mov_b64 s[0:1], -1
	s_cbranch_scc0 .LBB0_539
	s_waitcnt vmcnt(0)
	s_waitcnt lgkmcnt(0)
	s_barrier
	s_mov_b64 s[0:1], exec
	v_readlane_b32 s40, v252, 21
	v_readlane_b32 s41, v252, 22
	s_and_b64 s[40:41], s[0:1], s[40:41]
	s_mov_b64 exec, s[40:41]
	s_cbranch_execz .LBB0_538
	s_mov_b64 s[40:41], src_shared_base
	v_mov_b32_e32 v199, s41
	s_waitcnt vmcnt(0) expcnt(0) lgkmcnt(0)
	flat_load_dword v2, v[198:199] sc0 sc1
	v_mov_b32_e32 v201, s41
	flat_load_dword v0, v[200:201] sc0 sc1
	s_waitcnt vmcnt(0) lgkmcnt(0)
	v_cmp_eq_u32_e32 vcc, 0, v2
	s_and_saveexec_b64 s[40:41], vcc
	s_cbranch_execz .LBB0_502
	s_mov_b32 s25, 1
	s_branch .LBB0_490

.LBB0_605:
	v_readlane_b32 s0, v254, 49
	s_cmp_gt_i32 s0, -1
	s_mov_b64 s[0:1], -1
	s_cbranch_scc0 .LBB0_659
	s_waitcnt vmcnt(0)
	s_waitcnt vmcnt(63) expcnt(7) lgkmcnt(15)
	s_barrier
	s_mov_b64 s[0:1], exec
	v_readlane_b32 s40, v252, 21
	v_readlane_b32 s41, v252, 22
	s_and_b64 s[40:41], s[0:1], s[40:41]
	s_mov_b64 exec, s[40:41]
	s_cbranch_execz .LBB0_658
	s_mov_b64 s[40:41], src_shared_base
	v_mov_b32_e32 v199, s41
	s_waitcnt vmcnt(0) expcnt(0) lgkmcnt(0)
	flat_load_dword v2, v[198:199] sc0 sc1
	v_mov_b32_e32 v201, s41
	flat_load_dword v0, v[200:201] sc0 sc1
	s_waitcnt vmcnt(0) lgkmcnt(0)
	v_cmp_eq_u32_e32 vcc, 0, v2
	s_and_saveexec_b64 s[40:41], vcc
	s_cbranch_execz .LBB0_622
	s_mov_b32 s25, 1
	s_branch .LBB0_610

.LBB0_808:
	v_readlane_b32 s0, v254, 49
	s_cmp_gt_i32 s0, -2
	s_mov_b64 s[0:1], -1
	s_cbranch_scc0 .LBB0_862
	s_waitcnt vmcnt(0)
	s_waitcnt lgkmcnt(0)
	s_barrier
	s_mov_b64 s[0:1], exec
	v_readlane_b32 s40, v252, 21
	v_readlane_b32 s41, v252, 22
	s_and_b64 s[40:41], s[0:1], s[40:41]
	s_mov_b64 exec, s[40:41]
	s_cbranch_execz .LBB0_861
	s_mov_b64 s[40:41], src_shared_base
	v_mov_b32_e32 v199, s41
	s_waitcnt vmcnt(0) expcnt(0) lgkmcnt(0)
	flat_load_dword v2, v[198:199] sc0 sc1
	v_mov_b32_e32 v201, s41
	flat_load_dword v0, v[200:201] sc0 sc1
	s_waitcnt vmcnt(0) lgkmcnt(0)
	v_cmp_eq_u32_e32 vcc, 0, v2
	s_and_saveexec_b64 s[40:41], vcc
	s_cbranch_execz .LBB0_825
	s_mov_b32 s25, 1
	s_branch .LBB0_813

.LBB0_888:
	s_cmp_gt_i32 s64, 1
	s_mov_b64 s[0:1], -1
	s_cbranch_scc0 .LBB0_942
	s_waitcnt vmcnt(0)
	s_barrier
	s_mov_b64 s[0:1], exec
	v_readlane_b32 s10, v252, 21
	v_readlane_b32 s11, v252, 22
	s_and_b64 s[10:11], s[0:1], s[10:11]
	s_mov_b64 exec, s[10:11]
	s_cbranch_execz .LBB0_941
	s_mov_b64 s[10:11], src_shared_base
	v_mov_b32_e32 v199, s11
	s_waitcnt vmcnt(0) expcnt(0) lgkmcnt(0)
	flat_load_dword v2, v[198:199] sc0 sc1
	v_mov_b32_e32 v201, s11
	flat_load_dword v0, v[200:201] sc0 sc1
	s_waitcnt vmcnt(0) lgkmcnt(0)
	v_cmp_eq_u32_e32 vcc, 0, v2
	s_and_saveexec_b64 s[10:11], vcc
	s_cbranch_execz .LBB0_905
	s_mov_b32 s25, 1
	s_branch .LBB0_893

.LBB0_998:
	s_cbranch_execz .LBB0_956
	s_cmp_gt_i32 s64, 0
	s_mov_b64 s[0:1], -1
	s_cbranch_scc0 .LBB0_1053
	s_waitcnt vmcnt(0)
	s_waitcnt vmcnt(0) lgkmcnt(0)
	s_barrier
	s_mov_b64 s[0:1], exec
	v_readlane_b32 s10, v252, 21
	v_readlane_b32 s11, v252, 22
	s_and_b64 s[10:11], s[0:1], s[10:11]
	s_mov_b64 exec, s[10:11]
	s_cbranch_execz .LBB0_1052
	s_mov_b64 s[10:11], src_shared_base
	v_mov_b32_e32 v199, s11
	s_waitcnt vmcnt(0) expcnt(0) lgkmcnt(0)
	flat_load_dword v2, v[198:199] sc0 sc1
	v_mov_b32_e32 v201, s11
	flat_load_dword v0, v[200:201] sc0 sc1
	s_waitcnt vmcnt(0) lgkmcnt(0)
	v_cmp_eq_u32_e32 vcc, 0, v2
	s_and_saveexec_b64 s[10:11], vcc
	s_cbranch_execz .LBB0_1016
	s_mov_b32 s25, 1
	s_branch .LBB0_1004

.LBB0_1074:
	s_cmp_gt_i32 s64, -1
	s_mov_b64 s[0:1], -1
	s_cbranch_scc0 .LBB0_1128
	s_waitcnt vmcnt(0)
	s_barrier
	s_mov_b64 s[0:1], exec
	v_readlane_b32 s40, v252, 21
	v_readlane_b32 s41, v252, 22
	s_and_b64 s[40:41], s[0:1], s[40:41]
	s_mov_b64 exec, s[40:41]
	s_cbranch_execz .LBB0_1127
	s_mov_b64 s[40:41], src_shared_base
	v_mov_b32_e32 v199, s41
	s_waitcnt vmcnt(0) expcnt(0) lgkmcnt(0)
	flat_load_dword v2, v[198:199] sc0 sc1
	v_mov_b32_e32 v201, s41
	flat_load_dword v0, v[200:201] sc0 sc1
	s_waitcnt vmcnt(0) lgkmcnt(0)
	v_cmp_eq_u32_e32 vcc, 0, v2
	s_and_saveexec_b64 s[40:41], vcc
	s_cbranch_execz .LBB0_1091
	s_mov_b32 s34, 1
	s_branch .LBB0_1079

.LBB0_1174:
	s_cbranch_execz .LBB0_1142
	s_cmp_gt_i32 s64, -2
	s_mov_b64 s[0:1], -1
	s_cbranch_scc0 .LBB0_1229
	s_waitcnt vmcnt(0)
	s_waitcnt vmcnt(0) lgkmcnt(0)
	s_barrier
	s_mov_b64 s[0:1], exec
	v_readlane_b32 s40, v252, 21
	v_readlane_b32 s41, v252, 22
	s_and_b64 s[40:41], s[0:1], s[40:41]
	s_mov_b64 exec, s[40:41]
	s_cbranch_execz .LBB0_1228
	s_mov_b64 s[40:41], src_shared_base
	v_mov_b32_e32 v199, s41
	s_waitcnt vmcnt(0) expcnt(0) lgkmcnt(0)
	flat_load_dword v2, v[198:199] sc0 sc1
	v_mov_b32_e32 v201, s41
	flat_load_dword v0, v[200:201] sc0 sc1
	s_waitcnt vmcnt(0) lgkmcnt(0)
	v_cmp_eq_u32_e32 vcc, 0, v2
	s_and_saveexec_b64 s[40:41], vcc
	s_cbranch_execz .LBB0_1192
	s_mov_b32 s34, 1
	s_branch .LBB0_1180

.LBB0_1285:
	s_cbranch_execz .LBB0_1243
	s_cmp_gt_i32 s64, -3
	s_mov_b64 s[0:1], -1
	s_cbranch_scc0 .LBB0_1340
	s_waitcnt vmcnt(0)
	s_waitcnt vmcnt(0) lgkmcnt(0)
	s_barrier
	s_mov_b64 s[0:1], exec
	v_readlane_b32 s40, v252, 21
	v_readlane_b32 s41, v252, 22
	s_and_b64 s[40:41], s[0:1], s[40:41]
	s_mov_b64 exec, s[40:41]
	s_cbranch_execz .LBB0_1339
	s_mov_b64 s[40:41], src_shared_base
	v_mov_b32_e32 v199, s41
	s_waitcnt vmcnt(0) expcnt(0) lgkmcnt(0)
	flat_load_dword v2, v[198:199] sc0 sc1
	v_mov_b32_e32 v201, s41
	flat_load_dword v0, v[200:201] sc0 sc1
	s_waitcnt vmcnt(0) lgkmcnt(0)
	v_cmp_eq_u32_e32 vcc, 0, v2
	s_and_saveexec_b64 s[40:41], vcc
	s_cbranch_execz .LBB0_1303
	s_mov_b32 s34, 1
	s_branch .LBB0_1291

.LBB0_1388:
	v_readlane_b32 s52, v254, 47
	s_cmp_gt_i32 s64, -4
	s_mov_b64 s[0:1], -1
	v_readlane_b32 s53, v254, 48
	s_cbranch_scc0 .LBB0_1442
	s_waitcnt vmcnt(0)
	s_barrier
	s_mov_b64 s[0:1], exec
	v_readlane_b32 s10, v252, 21
	v_readlane_b32 s11, v252, 22
	s_and_b64 s[10:11], s[0:1], s[10:11]
	s_mov_b64 exec, s[10:11]
	s_cbranch_execz .LBB0_1441
	s_mov_b64 s[10:11], src_shared_base
	v_mov_b32_e32 v199, s11
	s_waitcnt vmcnt(0) expcnt(0) lgkmcnt(0)
	flat_load_dword v2, v[198:199] sc0 sc1
	v_mov_b32_e32 v201, s11
	flat_load_dword v0, v[200:201] sc0 sc1
	s_waitcnt vmcnt(0) lgkmcnt(0)
	v_cmp_eq_u32_e32 vcc, 0, v2
	s_and_saveexec_b64 s[10:11], vcc
	s_cbranch_execz .LBB0_1405
	s_mov_b32 s25, 1
	s_branch .LBB0_1393
